# v8 + static s_setprio 1 for waves 4-7 during attention units (timing only)
# baseline (speedup 1.0000x reference)
; DI void attn_unit(LAS unsigned char* lds, int tid, const bf16* __restrict__ P, const bf16* __restrict__ Vt, bf16* MG, int b, int h, int qrow0, int jt0, int jt1,
;                   float lam, float oscale, const float* subg) {
;     ...
;     const bool halfB = wave >= 4;
; __global__ void __launch_bounds__(NTHREADS, 2) mega(Args A) {
;     ...
;             if (PEN(7)) for (int rp_ = 0; rp_ < REP_ATTN; ++rp_) for (int u = bid; u < 256; u += G) { const int bh = r * 8 + (u & 7), qb = u >> 3;
;                 attn_unit(lds, tid, HP, Vt, Abuf, bh >> 2, bh & 3, (bh >> 2) * SEQ + qb * 128, 0, 68, lam, 1.0f - lam_init, subg); }
.LBB0_295:
	v_readfirstlane_b32 s0, v152
	s_nop 3
	s_bfe_u32 s0, s0, 0x20008
	s_cmp_lg_u32 s0, 0
	s_cbranch_scc0 .Lprio_att_done
	s_setprio 1

; DI void s2_phase(const ScanCtx& C, int tid, int bid, int G) {
; #pragma unroll 1
;     for (int gt = bid * NTHREADS + tid; gt < 65536 + 32768; gt += G * NTHREADS) s2_item(C, gt);
; __global__ void __launch_bounds__(NTHREADS, 2) mega(Args A) {
;     ...
;             if (is_conv) {
;                 if (PEN(10)) conv_phase(HP, (bf16*)(ws + WS_U), C.cw, C.cb, tid, bid, G);
;             } else if (s == 4) {
;                 { const int nS1 = NB * NVC, extra1 = (nS1 > G && nS1 < 2 * G) ? nS1 - G : 0;
;                   if (PEN(5)) { for (int u = bid; u < nS1; u += G) s1_ssd_unit(lds, tid, C, u / NVC, u % NVC);
;                       if (bid >= extra1) for (int r = bid - extra1; r < 4 * nS1; r += G - extra1) { const int v = r >> 2; s1_ret_unit(lds, tid, C, v / NVC, v % NVC, r & 3, 1); } } }
;             } else if (s == 5) {
;                 if (PEN(6)) s2_phase(C, tid, bid, G);
.LBB0_318:
	s_setprio 0
	v_readlane_b32 s0, v253, 42
	s_add_u32 s28, s0, 0x1bf00000
	v_readlane_b32 s0, v253, 43
	s_addc_u32 s29, s0, 0
	s_mov_b64 s[0:1], -1
	s_and_b64 vcc, exec, s[10:11]
	s_cbranch_vccz .LBB0_809
	v_readlane_b32 s0, v253, 42
	s_add_u32 s2, s0, 0x400000
	v_readlane_b32 s1, v253, 43
	s_addc_u32 s3, s1, 0
	s_add_u32 s30, s0, 0x18c00000
	v_writelane_b32 v253, s2, 49
	s_addc_u32 s31, s1, 0
	v_readlane_b32 s4, v252, 10
	v_writelane_b32 v253, s3, 50
	s_add_u32 s2, s0, 0x1ae00000
	s_addc_u32 s3, s1, 0
	v_writelane_b32 v253, s2, 51
	s_add_u32 s0, s0, 0x500000
	s_addc_u32 s1, s1, 0
	v_writelane_b32 v253, s3, 52
	v_writelane_b32 v253, s0, 53
	v_readlane_b32 s16, v252, 22
	v_readlane_b32 s17, v252, 23
	v_writelane_b32 v253, s1, 54
	v_readlane_b32 s18, v252, 24
	v_readlane_b32 s0, v253, 35
	v_readlane_b32 s1, v253, 36
	s_lshl_b32 s0, s0, 3
	s_ashr_i32 s1, s0, 31
	s_lshl_b64 s[0:1], s[0:1], 2
	s_add_u32 s2, s16, s0
	s_addc_u32 s3, s17, s1
	v_writelane_b32 v253, s2, 55
	v_readlane_b32 s5, v252, 11
	v_readlane_b32 s6, v252, 12
	v_readlane_b32 s7, v252, 13
	v_readlane_b32 s8, v252, 14
	v_readlane_b32 s9, v252, 15
	v_readlane_b32 s10, v252, 16
	v_readlane_b32 s11, v252, 17
	v_readlane_b32 s19, v252, 25
	v_writelane_b32 v253, s3, 56
	s_add_u32 s2, s18, s0
	s_addc_u32 s3, s19, s1
	v_readlane_b32 s4, v252, 46
	v_writelane_b32 v253, s2, 57
	v_readlane_b32 s8, v252, 50
	v_readlane_b32 s9, v252, 51
	v_writelane_b32 v253, s3, 58
	s_add_u32 s2, s8, s0
	s_addc_u32 s3, s9, s1
	v_readlane_b32 s5, v252, 47
	v_readlane_b32 s6, v252, 48
	v_readlane_b32 s7, v252, 49
	v_writelane_b32 v253, s2, 59
	s_mov_b64 s[6:7], -1
	s_cmp_lt_i32 s34, 5
	v_writelane_b32 v253, s3, 60
	s_mov_b64 s[2:3], 0
	s_mov_b64 s[4:5], 0
	v_readlane_b32 s12, v252, 18
	v_readlane_b32 s13, v252, 19
	v_readlane_b32 s14, v252, 20
	v_readlane_b32 s15, v252, 21
	v_readlane_b32 s10, v252, 52
	v_readlane_b32 s11, v252, 53
	s_cbranch_scc1 .LBB0_343
	s_cmp_eq_u32 s34, 5
	s_mov_b64 s[4:5], -1
	s_cbranch_scc0 .LBB0_347
	v_readlane_b32 s4, v253, 33
	s_nop 1
	v_lshl_add_u32 v61, s4, 9, v152
	s_mov_b32 s4, 0x18000
	v_cmp_gt_i32_e32 vcc, s4, v61
	s_and_saveexec_b64 s[4:5], vcc
	s_cbranch_execz .LBB0_346
	v_readlane_b32 s6, v253, 34
	s_lshl_b32 s10, s6, 9
	s_mov_b64 s[6:7], 0
	s_branch .LBB0_324
